# head-split QK block plus raised wave priority over the QK MFMA block
# speedup vs baseline: 1.0029x; 1.0029x over previous
.LBB0_883:
	s_andn2_b64 vcc, exec, s[28:29]
	s_cbranch_vccnz .LBB0_885
	v_mad_u32_u24 v203, v203, s82, v201
	ds_read_b128 v[204:207], v203
	ds_read_b128 v[208:211], v203 offset:32
	s_nop 5
	v_xor_b32_e32 v80, 0x80000000, v199
	v_mov_b32_e32 v81, v80
	v_mov_b32_e32 v82, v80
	v_mov_b32_e32 v83, v80
	v_mov_b32_e32 v84, v80
	v_mov_b32_e32 v85, v80
	v_mov_b32_e32 v86, v80
	v_mov_b32_e32 v87, v80
	v_mov_b32_e32 v88, v80
	v_mov_b32_e32 v89, v80
	v_mov_b32_e32 v90, v80
	v_mov_b32_e32 v91, v80
	v_mov_b32_e32 v92, v80
	v_mov_b32_e32 v93, v80
	v_mov_b32_e32 v94, v80
	v_mov_b32_e32 v95, v80
	s_waitcnt lgkmcnt(0)
	s_setprio 1
	v_mfma_f32_32x32x16_bf16 v[80:95], v[204:207], v[96:99], v[80:95]
	v_xor_b32_e32 v64, 0x80000000, v200
	v_mov_b32_e32 v65, v64
	v_mov_b32_e32 v66, v64
	v_mov_b32_e32 v67, v64
	v_mov_b32_e32 v68, v64
	v_mov_b32_e32 v69, v64
	v_mov_b32_e32 v70, v64
	v_mov_b32_e32 v71, v64
	v_mov_b32_e32 v72, v64
	v_mov_b32_e32 v73, v64
	v_mov_b32_e32 v74, v64
	v_mov_b32_e32 v75, v64
	v_mov_b32_e32 v76, v64
	v_mov_b32_e32 v77, v64
	v_mov_b32_e32 v78, v64
	v_mov_b32_e32 v79, v64
	v_mfma_f32_32x32x16_bf16 v[64:79], v[204:207], v[136:139], v[64:79]
	v_mfma_f32_32x32x16_bf16 v[80:95], v[208:211], v[100:103], v[80:95]
	v_mfma_f32_32x32x16_bf16 v[64:79], v[208:211], v[120:123], v[64:79]
	ds_read_b128 v[204:207], v203 offset:64
	ds_read_b128 v[208:211], v203 offset:96
	s_waitcnt lgkmcnt(0)
	v_mfma_f32_32x32x16_bf16 v[80:95], v[204:207], v[104:107], v[80:95]
	v_mfma_f32_32x32x16_bf16 v[64:79], v[204:207], v[124:127], v[64:79]
	v_mfma_f32_32x32x16_bf16 v[80:95], v[208:211], v[108:111], v[80:95]
	v_mfma_f32_32x32x16_bf16 v[64:79], v[208:211], v[128:131], v[64:79]
	ds_read_b128 v[204:207], v203 offset:128
	ds_read_b128 v[208:211], v203 offset:160
	s_waitcnt lgkmcnt(0)
	v_mfma_f32_32x32x16_bf16 v[80:95], v[204:207], v[112:115], v[80:95]
	v_mfma_f32_32x32x16_bf16 v[64:79], v[204:207], v[132:135], v[64:79]
	v_mfma_f32_32x32x16_bf16 v[80:95], v[208:211], v[116:119], v[80:95]
	v_mfma_f32_32x32x16_bf16 v[64:79], v[208:211], v[140:143], v[64:79]
	s_setprio 0
	s_branch .LBB0_885

.LBB0_2117:
	s_andn2_b64 vcc, exec, s[34:35]
	s_cbranch_vccnz .LBB0_2119
	v_mad_u32_u24 v203, v203, s81, v201
	ds_read_b128 v[204:207], v203
	ds_read_b128 v[208:211], v203 offset:32
	s_nop 5
	v_xor_b32_e32 v80, 0x80000000, v199
	v_mov_b32_e32 v81, v80
	v_mov_b32_e32 v82, v80
	v_mov_b32_e32 v83, v80
	v_mov_b32_e32 v84, v80
	v_mov_b32_e32 v85, v80
	v_mov_b32_e32 v86, v80
	v_mov_b32_e32 v87, v80
	v_mov_b32_e32 v88, v80
	v_mov_b32_e32 v89, v80
	v_mov_b32_e32 v90, v80
	v_mov_b32_e32 v91, v80
	v_mov_b32_e32 v92, v80
	v_mov_b32_e32 v93, v80
	v_mov_b32_e32 v94, v80
	v_mov_b32_e32 v95, v80
	s_waitcnt lgkmcnt(0)
	s_setprio 1
	v_mfma_f32_32x32x16_bf16 v[80:95], v[204:207], v[96:99], v[80:95]
	v_xor_b32_e32 v64, 0x80000000, v200
	v_mov_b32_e32 v65, v64
	v_mov_b32_e32 v66, v64
	v_mov_b32_e32 v67, v64
	v_mov_b32_e32 v68, v64
	v_mov_b32_e32 v69, v64
	v_mov_b32_e32 v70, v64
	v_mov_b32_e32 v71, v64
	v_mov_b32_e32 v72, v64
	v_mov_b32_e32 v73, v64
	v_mov_b32_e32 v74, v64
	v_mov_b32_e32 v75, v64
	v_mov_b32_e32 v76, v64
	v_mov_b32_e32 v77, v64
	v_mov_b32_e32 v78, v64
	v_mov_b32_e32 v79, v64
	v_mfma_f32_32x32x16_bf16 v[64:79], v[204:207], v[136:139], v[64:79]
	v_mfma_f32_32x32x16_bf16 v[80:95], v[208:211], v[100:103], v[80:95]
	v_mfma_f32_32x32x16_bf16 v[64:79], v[208:211], v[120:123], v[64:79]
	ds_read_b128 v[204:207], v203 offset:64
	ds_read_b128 v[208:211], v203 offset:96
	s_waitcnt lgkmcnt(0)
	v_mfma_f32_32x32x16_bf16 v[80:95], v[204:207], v[104:107], v[80:95]
	v_mfma_f32_32x32x16_bf16 v[64:79], v[204:207], v[124:127], v[64:79]
	v_mfma_f32_32x32x16_bf16 v[80:95], v[208:211], v[108:111], v[80:95]
	v_mfma_f32_32x32x16_bf16 v[64:79], v[208:211], v[128:131], v[64:79]
	ds_read_b128 v[204:207], v203 offset:128
	ds_read_b128 v[208:211], v203 offset:160
	s_waitcnt lgkmcnt(0)
	v_mfma_f32_32x32x16_bf16 v[80:95], v[204:207], v[112:115], v[80:95]
	v_mfma_f32_32x32x16_bf16 v[64:79], v[204:207], v[132:135], v[64:79]
	v_mfma_f32_32x32x16_bf16 v[80:95], v[208:211], v[116:119], v[80:95]
	v_mfma_f32_32x32x16_bf16 v[64:79], v[208:211], v[140:143], v[64:79]
	s_setprio 0
	s_branch .LBB0_2119
